# v16 + layer-1 S5 lag-kernel table build: the four b_bar rows of a state block requested together instead of one load-wait round trip each
# speedup vs baseline: 1.0101x; 1.0101x over previous
; __device__ __forceinline__ void ssm_build_mef(const Params& p, const Ctx& c, int l) {
;     ...
;   for (long i = c.gtid; i < 32L * 2 * 32 * 256; i += c.nthr) { const int hp = (int)(i & 15), h = (int)((i >> 4) & 15), j = (int)((i >> 8) & 31), gd = (int)(i >> 13), d = gd & 1, g = gd >> 1;
;     const size_t ci = ((size_t)((l * 2 + d) * 32 + g) * 16 + h) * 64; const float2* pw = PW + ((size_t)gd * 33 + j) * 64; const float2* bb = BB + (size_t)gd * 64 * 16 + hp; float a = 0.f;
;     for (int pp = 0; pp < 64; ++pp) { const float cr = p.ssm_c_re[ci + pp], cim = p.ssm_c_im[ci + pp]; const float2 b = bb[pp * 16], w = pw[pp];
;       const float wr = cr * b.x - cim * b.y, wi = cr * b.y + cim * b.x; a += wr * w.x - wi * w.y; }
;     MK[i] = a; }
.LBB0_967:
	v_lshl_add_u64 v[16:17], v[14:15], 0, s[62:63]
	global_load_dwordx4 v[22:25], v[16:17], off
	v_lshl_add_u64 v[16:17], v[12:13], 0, s[62:63]
	global_load_dwordx4 v[26:29], v[16:17], off
	v_lshl_add_u64 v[16:17], s[54:55], 0, v[8:9]
	v_add_co_u32_e32 v16, vcc, 0xac4c000, v16
	v_lshl_add_u64 v[30:31], s[54:55], 0, v[10:11]
	s_nop 0
	v_addc_co_u32_e32 v17, vcc, 0, v17, vcc
	global_load_dwordx2 v[38:39], v[16:17], off
	global_load_dwordx2 v[60:61], v[16:17], off offset:128
	global_load_dwordx2 v[62:63], v[16:17], off offset:256
	global_load_dwordx2 v[64:65], v[16:17], off offset:384
	s_mov_b64 s[0:1], 0xaac4000
	v_lshl_add_u64 v[34:35], v[30:31], 0, s[0:1]
	v_add_co_u32_e32 v30, vcc, 0xaac4000, v30
	s_add_u32 s62, s62, 16
	s_nop 0
	v_addc_co_u32_e32 v31, vcc, 0, v31, vcc
	global_load_dwordx4 v[30:33], v[30:31], off
	s_nop 0
	global_load_dwordx4 v[34:37], v[34:35], off offset:16
	s_mov_b64 s[0:1], 0x200
	s_addc_u32 s63, s63, 0
	v_lshl_add_u64 v[8:9], v[8:9], 0, s[0:1]
	v_lshl_add_u64 v[10:11], v[10:11], 0, 32
	s_cmpk_eq_i32 s62, 0x100
	s_waitcnt vmcnt(5)
	v_pk_mul_f32 v[40:41], v[26:27], v[38:39] op_sel:[0,1] op_sel_hi:[0,0]
	v_pk_fma_f32 v[42:43], v[22:23], v[38:39], v[40:41] neg_lo:[0,0,1] neg_hi:[0,0,1]
	v_pk_fma_f32 v[38:39], v[22:23], v[38:39], v[40:41] op_sel_hi:[0,1,1]
	v_mov_b32_e32 v43, v39
	v_mov_b32_e32 v38, v23
	s_waitcnt vmcnt(1)
	v_pk_mul_f32 v[30:31], v[30:31], v[42:43]
	s_nop 0
	v_sub_f32_e32 v30, v30, v31
	v_add_f32_e32 v1, v1, v30
	s_waitcnt vmcnt(0)
	v_mov_b64_e32 v[30:31], v[60:61]
	v_pk_mul_f32 v[26:27], v[26:27], v[30:31] op_sel:[1,1] op_sel_hi:[1,0]
	s_nop 0
	v_pk_fma_f32 v[38:39], v[38:39], v[30:31], v[26:27] neg_lo:[0,0,1] neg_hi:[0,0,1]
	v_pk_fma_f32 v[22:23], v[22:23], v[30:31], v[26:27] op_sel:[1,0,0]
	s_nop 0
	v_mov_b32_e32 v39, v23
	v_pk_mul_f32 v[22:23], v[32:33], v[38:39]
	s_nop 0
	v_sub_f32_e32 v22, v22, v23
	v_add_f32_e32 v1, v1, v22
	s_waitcnt vmcnt(0)
	v_mov_b64_e32 v[22:23], v[62:63]
	v_pk_mul_f32 v[26:27], v[28:29], v[22:23] op_sel:[0,1] op_sel_hi:[0,0]
	v_mov_b64_e32 v[16:17], v[64:65]
	v_pk_fma_f32 v[30:31], v[24:25], v[22:23], v[26:27] neg_lo:[0,0,1] neg_hi:[0,0,1]
	v_pk_fma_f32 v[22:23], v[24:25], v[22:23], v[26:27] op_sel_hi:[0,1,1]
	v_mov_b32_e32 v31, v23
	v_pk_mul_f32 v[22:23], v[34:35], v[30:31]
	v_mov_b32_e32 v26, v29
	v_sub_f32_e32 v22, v22, v23
	v_add_f32_e32 v1, v1, v22
	v_mov_b32_e32 v22, v25
	v_mov_b32_e32 v24, v25
	s_waitcnt vmcnt(0)
	v_pk_mul_f32 v[26:27], v[26:27], v[16:17] op_sel:[0,1] op_sel_hi:[0,0]
	v_pk_fma_f32 v[22:23], v[22:23], v[16:17], v[26:27] neg_lo:[0,0,1] neg_hi:[0,0,1]
	v_pk_fma_f32 v[16:17], v[24:25], v[16:17], v[26:27] op_sel_hi:[0,1,1]
	v_mov_b32_e32 v23, v17
	v_pk_mul_f32 v[16:17], v[36:37], v[22:23]
	s_nop 0
	v_sub_f32_e32 v16, v16, v17
	v_add_f32_e32 v1, v1, v16
	s_cbranch_scc0 .LBB0_967
	v_lshl_add_u64 v[8:9], v[6:7], 2, s[56:57]
	v_lshl_add_u64 v[6:7], v[6:7], 0, s[22:23]
	v_readlane_b32 s0, v250, 5
	v_cmp_lt_i64_e32 vcc, s[70:71], v[6:7]
	v_readlane_b32 s1, v250, 6
	s_or_b64 s[60:61], vcc, s[60:61]
	global_store_dword v[8:9], v1, off
	v_lshl_add_u64 v[4:5], v[4:5], 0, s[0:1]
	s_andn2_b64 exec, exec, s[60:61]
	s_cbranch_execnz .LBB0_966
	s_or_b64 exec, exec, s[60:61]
	s_add_u32 s56, s54, 0xaac4000
	s_addc_u32 s57, s55, 0
	s_add_u32 s12, s54, 0xac4c000
	s_addc_u32 s13, s55, 0
	s_add_u32 s14, s54, 0xc8cc000
	s_addc_u32 s15, s55, 0
	s_lshl_b64 s[0:1], s[58:59], 12
	v_lshl_add_u64 v[22:23], v[2:3], 3, s[0:1]
	s_mov_b64 s[58:59], 0
	v_mov_b64_e32 v[24:25], v[18:19]
